# K-loop tail: counter update and exit compare moved in front of the closing s_barrier (loop-edge edit)
# baseline (speedup 1.0000x reference)
; #define PG8_STAGE(bufoff, gbase, voff) do { _Pragma("unroll") for (int _i = 0; _i < 2; ++_i) \
;         __builtin_amdgcn_global_load_lds((const unsigned*)((const char*)(gbase) + (voff)[_i]), (LAS unsigned*)(lds + (bufoff) + ldsw + _i * 8192), 16, 0, 0); } while (0)
; #define PG8_LDA(dst, b, h) do { _Pragma("unroll") for (int m = 0; m < 4; ++m) _Pragma("unroll") for (int k = 0; k < 2; ++k) dst[m][k] = *(const LAS bf16x8*)(lds + PG8_SA(b, h) + aoff + m * 2048 + k * 1024); } while (0)
; #define PG8_LDB(dst, b, h) do { _Pragma("unroll") for (int n = 0; n < 2; ++n) _Pragma("unroll") for (int k = 0; k < 2; ++k) dst[n][k] = *(const LAS bf16x8*)(lds + PG8_SB(b, h) + boff + n * 2048 + k * 1024); } while (0)
; #define PG8_MMA(ai, bj, At, Bt) do { __builtin_amdgcn_s_setprio(1); _Pragma("unroll") for (int m = 0; m < 4; ++m) _Pragma("unroll") for (int n = 0; n < 2; ++n) _Pragma("unroll") for (int k = 0; k < 2; ++k) \
;         acc[ai][bj][m][n] = __builtin_amdgcn_mfma_f32_16x16x32_bf16(Bt[n][k], At[m][k], acc[ai][bj][m][n], 0, 0, 0); __builtin_amdgcn_s_setprio(0); } while (0)
; #define PG8_WAIT_V(n) asm volatile("s_waitcnt vmcnt(" #n ")" ::: "memory")
; #define PG8_WAIT_L(n) asm volatile("s_waitcnt lgkmcnt(" #n ")" ::: "memory")
; #define PG8_BAR __builtin_amdgcn_s_barrier()
; #define PG8_SCHED __builtin_amdgcn_sched_barrier(0)
; DI void gemm_phase(LAS unsigned char* lds, const Sched& S, const Epi& Ep) {
;     ...
;             const char* a1 = cA + (size_t)(t + 1) * kstep;
;             const char* a2 = last ? nA : cA + (size_t)(t + 2) * kstep; const char* b2 = last ? nB : cB + (size_t)(t + 2) * kstep;
;             const char* a3 = a2 + kstep; const char* b3 = b2 + kstep;
;             PG8_LDB(B0, 0, 0); PG8_LDB(B1, 0, 1); PG8_SCHED; PG8_LDA(At, 0, 0); PG8_STAGE(PG8_SA(1, 1), a1 + hstepA, voffA);
;             PG8_WAIT_V(8); PG8_WAIT_L(0); PG8_BAR; PG8_MMA(0, 0, At, B0); PG8_MMA(0, 1, At, B1); PG8_BAR; PG8_SCHED;
;             PG8_LDA(At, 0, 1); PG8_STAGE(PG8_SB(0, 0), b2, voffB); PG8_STAGE(PG8_SB(0, 1), b2 + hstepB, voffB); PG8_STAGE(PG8_SA(0, 0), a2, voffA);
.LBB0_370:
	s_add_i32 s3, s3, 2
	s_add_u32 s8, s46, s44
	s_addc_u32 s12, s47, s45
	s_add_u32 s8, s8, 0x100
	s_addc_u32 s12, s12, 0
	s_add_u32 s24, s64, s44
	s_addc_u32 s13, s10, s45
	s_add_i32 s25, 0, 0x10000
	s_cmp_eq_u32 s7, s44
	s_cselect_b32 s17, s1, s12
	s_cselect_b32 s16, s0, s8
	v_add_u32_e32 v0, s25, v252
	s_cselect_b32 s13, s79, s13
	s_cselect_b32 s12, s78, s24
	s_add_i32 s8, 0, 0x14000
	ds_read_b128 v[134:137], v0
	ds_read_b128 v[138:141], v0 offset:1024
	ds_read_b128 v[142:145], v0 offset:2048
	ds_read_b128 v[146:149], v0 offset:3072
	v_add_u32_e32 v0, s8, v252
	ds_read_b128 v[150:153], v0
	ds_read_b128 v[154:157], v0 offset:1024
	ds_read_b128 v[158:161], v0 offset:2048
	ds_read_b128 v[162:165], v0 offset:3072
	v_lshl_add_u64 v[210:211], v[132:133], 0, s[44:45]
	s_add_i32 m0, s96, 0xc000
	ds_read_b128 v[166:169], v249
	ds_read_b128 v[170:173], v249 offset:1024
	ds_read_b128 v[174:177], v249 offset:2048
	ds_read_b128 v[178:181], v249 offset:3072
	ds_read_b128 v[182:185], v249 offset:4096
	ds_read_b128 v[186:189], v249 offset:5120
	ds_read_b128 v[190:193], v249 offset:6144
	ds_read_b128 v[206:209], v249 offset:7168
	global_load_lds_dwordx4 v[210:211], off
	v_lshl_add_u64 v[210:211], v[130:131], 0, s[44:45]
	s_add_i32 m0, s96, 0xe000
	s_nop 0
	global_load_lds_dwordx4 v[210:211], off
	s_waitcnt vmcnt(8)
	s_waitcnt lgkmcnt(0)
	s_barrier
	s_waitcnt lgkmcnt(0)
	v_mfma_f32_16x16x32_bf16 v[126:129], v[134:137], v[166:169], v[126:129]
	v_mfma_f32_16x16x32_bf16 v[122:125], v[142:145], v[166:169], v[122:125]
	v_mfma_f32_16x16x32_bf16 v[110:113], v[134:137], v[174:177], v[110:113]
	v_mfma_f32_16x16x32_bf16 v[106:109], v[142:145], v[174:177], v[106:109]
	v_mfma_f32_16x16x32_bf16 v[94:97], v[134:137], v[182:185], v[94:97]
	v_mfma_f32_16x16x32_bf16 v[90:93], v[142:145], v[182:185], v[90:93]
	v_mfma_f32_16x16x32_bf16 v[78:81], v[134:137], v[190:193], v[78:81]
	v_mfma_f32_16x16x32_bf16 v[74:77], v[142:145], v[190:193], v[74:77]
	v_mfma_f32_16x16x32_bf16 v[126:129], v[138:141], v[170:173], v[126:129]
	v_mfma_f32_16x16x32_bf16 v[122:125], v[146:149], v[170:173], v[122:125]
	v_mfma_f32_16x16x32_bf16 v[110:113], v[138:141], v[178:181], v[110:113]
	v_mfma_f32_16x16x32_bf16 v[106:109], v[146:149], v[178:181], v[106:109]
	v_mfma_f32_16x16x32_bf16 v[94:97], v[138:141], v[186:189], v[94:97]
	v_mfma_f32_16x16x32_bf16 v[90:93], v[146:149], v[186:189], v[90:93]
	v_mfma_f32_16x16x32_bf16 v[78:81], v[138:141], v[206:209], v[78:81]
	v_mfma_f32_16x16x32_bf16 v[74:77], v[146:149], v[206:209], v[74:77]
	v_mfma_f32_16x16x32_bf16 v[118:121], v[150:153], v[166:169], v[118:121]
	v_mfma_f32_16x16x32_bf16 v[114:117], v[158:161], v[166:169], v[114:117]
	v_mfma_f32_16x16x32_bf16 v[102:105], v[150:153], v[174:177], v[102:105]
	v_mfma_f32_16x16x32_bf16 v[98:101], v[158:161], v[174:177], v[98:101]
	v_mfma_f32_16x16x32_bf16 v[86:89], v[150:153], v[182:185], v[86:89]
	v_mfma_f32_16x16x32_bf16 v[82:85], v[158:161], v[182:185], v[82:85]
	v_mfma_f32_16x16x32_bf16 v[70:73], v[150:153], v[190:193], v[70:73]
	v_mfma_f32_16x16x32_bf16 v[66:69], v[158:161], v[190:193], v[66:69]
	v_mfma_f32_16x16x32_bf16 v[118:121], v[154:157], v[170:173], v[118:121]
	v_mfma_f32_16x16x32_bf16 v[114:117], v[162:165], v[170:173], v[114:117]
	v_mfma_f32_16x16x32_bf16 v[102:105], v[154:157], v[178:181], v[102:105]
	v_mfma_f32_16x16x32_bf16 v[98:101], v[162:165], v[178:181], v[98:101]
	v_mfma_f32_16x16x32_bf16 v[86:89], v[154:157], v[186:189], v[86:89]
	v_mfma_f32_16x16x32_bf16 v[82:85], v[162:165], v[186:189], v[82:85]
	v_mfma_f32_16x16x32_bf16 v[70:73], v[154:157], v[206:209], v[70:73]
	v_mfma_f32_16x16x32_bf16 v[66:69], v[162:165], v[206:209], v[66:69]
	s_barrier
	s_add_i32 s24, s25, s19
	v_lshl_add_u64 v[210:211], s[12:13], 0, v[196:197]
	s_mov_b32 m0, s24
	ds_read_b128 v[166:169], v249 offset:16384
	ds_read_b128 v[170:173], v249 offset:17408
	ds_read_b128 v[174:177], v249 offset:18432
	ds_read_b128 v[178:181], v249 offset:19456
	ds_read_b128 v[182:185], v249 offset:20480
	ds_read_b128 v[186:189], v249 offset:21504
	ds_read_b128 v[190:193], v249 offset:22528
	ds_read_b128 v[206:209], v249 offset:23552
	global_load_lds_dwordx4 v[210:211], off
	s_add_i32 m0, s24, 0x2000
	v_lshl_add_u64 v[212:213], s[12:13], 0, v[200:201]
	s_add_u32 s12, s12, s77
	s_addc_u32 s13, s13, 0
	s_add_i32 s8, s8, s19
	global_load_lds_dwordx4 v[212:213], off
	v_lshl_add_u64 v[214:215], s[12:13], 0, v[196:197]
	s_mov_b32 m0, s8
	v_lshl_add_u64 v[216:217], s[12:13], 0, v[200:201]
	global_load_lds_dwordx4 v[214:215], off
	s_add_i32 m0, s8, 0x2000
	v_lshl_add_u64 v[218:219], s[16:17], 0, v[194:195]
	global_load_lds_dwordx4 v[216:217], off
	s_mov_b32 m0, s96
	v_lshl_add_u64 v[220:221], s[16:17], 0, v[198:199]
	global_load_lds_dwordx4 v[218:219], off
	s_mov_b32 m0, s90
	s_nop 0
	global_load_lds_dwordx4 v[220:221], off
	s_waitcnt vmcnt(8)
	s_waitcnt lgkmcnt(0)
	s_barrier
; #define PG8_STAGE(bufoff, gbase, voff) do { _Pragma("unroll") for (int _i = 0; _i < 2; ++_i) \
;         __builtin_amdgcn_global_load_lds((const unsigned*)((const char*)(gbase) + (voff)[_i]), (LAS unsigned*)(lds + (bufoff) + ldsw + _i * 8192), 16, 0, 0); } while (0)
; #define PG8_LDA(dst, b, h) do { _Pragma("unroll") for (int m = 0; m < 4; ++m) _Pragma("unroll") for (int k = 0; k < 2; ++k) dst[m][k] = *(const LAS bf16x8*)(lds + PG8_SA(b, h) + aoff + m * 2048 + k * 1024); } while (0)
; #define PG8_LDB(dst, b, h) do { _Pragma("unroll") for (int n = 0; n < 2; ++n) _Pragma("unroll") for (int k = 0; k < 2; ++k) dst[n][k] = *(const LAS bf16x8*)(lds + PG8_SB(b, h) + boff + n * 2048 + k * 1024); } while (0)
; #define PG8_MMA(ai, bj, At, Bt) do { __builtin_amdgcn_s_setprio(1); _Pragma("unroll") for (int m = 0; m < 4; ++m) _Pragma("unroll") for (int n = 0; n < 2; ++n) _Pragma("unroll") for (int k = 0; k < 2; ++k) \
;         acc[ai][bj][m][n] = __builtin_amdgcn_mfma_f32_16x16x32_bf16(Bt[n][k], At[m][k], acc[ai][bj][m][n], 0, 0, 0); __builtin_amdgcn_s_setprio(0); } while (0)
; #define PG8_WAIT_V(n) asm volatile("s_waitcnt vmcnt(" #n ")" ::: "memory")
; #define PG8_WAIT_L(n) asm volatile("s_waitcnt lgkmcnt(" #n ")" ::: "memory")
; #define PG8_BAR __builtin_amdgcn_s_barrier()
; #define PG8_SCHED __builtin_amdgcn_sched_barrier(0)
; DI void gemm_phase(LAS unsigned char* lds, const Sched& S, const Epi& Ep) {
;     ...
;             PG8_WAIT_V(8); PG8_WAIT_L(0); PG8_BAR; PG8_MMA(1, 0, At, B0); PG8_MMA(1, 1, At, B1); PG8_BAR; PG8_SCHED;
;             PG8_LDB(B0, 1, 0); PG8_LDB(B1, 1, 1); PG8_SCHED; PG8_LDA(At, 1, 0); PG8_STAGE(PG8_SA(0, 1), a2 + hstepA, voffA);
;             PG8_WAIT_V(8); PG8_WAIT_L(0); PG8_BAR; PG8_MMA(0, 0, At, B0); PG8_MMA(0, 1, At, B1); PG8_BAR; PG8_SCHED;
	s_waitcnt lgkmcnt(0)
	v_mfma_f32_16x16x32_bf16 v[62:65], v[134:137], v[166:169], v[62:65]
	v_mfma_f32_16x16x32_bf16 v[58:61], v[142:145], v[166:169], v[58:61]
	v_mfma_f32_16x16x32_bf16 v[46:49], v[134:137], v[174:177], v[46:49]
	v_mfma_f32_16x16x32_bf16 v[42:45], v[142:145], v[174:177], v[42:45]
	v_mfma_f32_16x16x32_bf16 v[30:33], v[134:137], v[182:185], v[30:33]
	v_mfma_f32_16x16x32_bf16 v[26:29], v[142:145], v[182:185], v[26:29]
	v_mfma_f32_16x16x32_bf16 v[14:17], v[134:137], v[190:193], v[14:17]
	v_mfma_f32_16x16x32_bf16 v[10:13], v[142:145], v[190:193], v[10:13]
	v_mfma_f32_16x16x32_bf16 v[62:65], v[138:141], v[170:173], v[62:65]
	v_mfma_f32_16x16x32_bf16 v[58:61], v[146:149], v[170:173], v[58:61]
	v_mfma_f32_16x16x32_bf16 v[46:49], v[138:141], v[178:181], v[46:49]
	v_mfma_f32_16x16x32_bf16 v[42:45], v[146:149], v[178:181], v[42:45]
	v_mfma_f32_16x16x32_bf16 v[30:33], v[138:141], v[186:189], v[30:33]
	v_mfma_f32_16x16x32_bf16 v[26:29], v[146:149], v[186:189], v[26:29]
	v_mfma_f32_16x16x32_bf16 v[14:17], v[138:141], v[206:209], v[14:17]
	v_mfma_f32_16x16x32_bf16 v[10:13], v[146:149], v[206:209], v[10:13]
	v_mfma_f32_16x16x32_bf16 v[54:57], v[150:153], v[166:169], v[54:57]
	v_mfma_f32_16x16x32_bf16 v[50:53], v[158:161], v[166:169], v[50:53]
	v_mfma_f32_16x16x32_bf16 v[38:41], v[150:153], v[174:177], v[38:41]
	v_mfma_f32_16x16x32_bf16 v[34:37], v[158:161], v[174:177], v[34:37]
	v_mfma_f32_16x16x32_bf16 v[22:25], v[150:153], v[182:185], v[22:25]
	v_mfma_f32_16x16x32_bf16 v[18:21], v[158:161], v[182:185], v[18:21]
	v_mfma_f32_16x16x32_bf16 v[6:9], v[150:153], v[190:193], v[6:9]
	v_mfma_f32_16x16x32_bf16 v[2:5], v[158:161], v[190:193], v[2:5]
	v_mfma_f32_16x16x32_bf16 v[54:57], v[154:157], v[170:173], v[54:57]
	v_mfma_f32_16x16x32_bf16 v[50:53], v[162:165], v[170:173], v[50:53]
	v_mfma_f32_16x16x32_bf16 v[38:41], v[154:157], v[178:181], v[38:41]
	v_mfma_f32_16x16x32_bf16 v[34:37], v[162:165], v[178:181], v[34:37]
	v_mfma_f32_16x16x32_bf16 v[22:25], v[154:157], v[186:189], v[22:25]
	v_mfma_f32_16x16x32_bf16 v[18:21], v[162:165], v[186:189], v[18:21]
	v_mfma_f32_16x16x32_bf16 v[6:9], v[154:157], v[206:209], v[6:9]
	v_mfma_f32_16x16x32_bf16 v[2:5], v[162:165], v[206:209], v[2:5]
	s_barrier
	s_add_i32 s8, 0, 0x18000
	v_add_u32_e32 v0, s8, v252
	s_add_i32 s24, 0, 0x1c000
	ds_read_b128 v[134:137], v0
	ds_read_b128 v[138:141], v0 offset:1024
	ds_read_b128 v[142:145], v0 offset:2048
	ds_read_b128 v[146:149], v0 offset:3072
	v_add_u32_e32 v0, s24, v252
	ds_read_b128 v[150:153], v0
	ds_read_b128 v[154:157], v0 offset:1024
	ds_read_b128 v[158:161], v0 offset:2048
	ds_read_b128 v[162:165], v0 offset:3072
	s_add_u32 s12, s16, s6
	s_addc_u32 s13, s17, 0
	s_mov_b32 m0, s91
	v_lshl_add_u64 v[222:223], s[12:13], 0, v[194:195]
	ds_read_b128 v[166:169], v249 offset:32768
	ds_read_b128 v[170:173], v249 offset:33792
	ds_read_b128 v[174:177], v249 offset:34816
	ds_read_b128 v[178:181], v249 offset:35840
	ds_read_b128 v[182:185], v249 offset:36864
	ds_read_b128 v[186:189], v249 offset:37888
	ds_read_b128 v[190:193], v249 offset:38912
	ds_read_b128 v[206:209], v249 offset:39936
	global_load_lds_dwordx4 v[222:223], off
	v_lshl_add_u64 v[222:223], s[12:13], 0, v[198:199]
	s_mov_b32 m0, s28
	s_nop 0
	global_load_lds_dwordx4 v[222:223], off
	s_waitcnt vmcnt(8)
	s_waitcnt lgkmcnt(0)
	s_barrier
	s_waitcnt lgkmcnt(0)
	v_mfma_f32_16x16x32_bf16 v[126:129], v[134:137], v[166:169], v[126:129]
	v_mfma_f32_16x16x32_bf16 v[122:125], v[142:145], v[166:169], v[122:125]
	v_mfma_f32_16x16x32_bf16 v[110:113], v[134:137], v[174:177], v[110:113]
	v_mfma_f32_16x16x32_bf16 v[106:109], v[142:145], v[174:177], v[106:109]
	v_mfma_f32_16x16x32_bf16 v[94:97], v[134:137], v[182:185], v[94:97]
	v_mfma_f32_16x16x32_bf16 v[90:93], v[142:145], v[182:185], v[90:93]
	v_mfma_f32_16x16x32_bf16 v[78:81], v[134:137], v[190:193], v[78:81]
	v_mfma_f32_16x16x32_bf16 v[74:77], v[142:145], v[190:193], v[74:77]
	v_mfma_f32_16x16x32_bf16 v[126:129], v[138:141], v[170:173], v[126:129]
	v_mfma_f32_16x16x32_bf16 v[122:125], v[146:149], v[170:173], v[122:125]
	v_mfma_f32_16x16x32_bf16 v[110:113], v[138:141], v[178:181], v[110:113]
	v_mfma_f32_16x16x32_bf16 v[106:109], v[146:149], v[178:181], v[106:109]
	v_mfma_f32_16x16x32_bf16 v[94:97], v[138:141], v[186:189], v[94:97]
	v_mfma_f32_16x16x32_bf16 v[90:93], v[146:149], v[186:189], v[90:93]
	v_mfma_f32_16x16x32_bf16 v[78:81], v[138:141], v[206:209], v[78:81]
	v_mfma_f32_16x16x32_bf16 v[74:77], v[146:149], v[206:209], v[74:77]
	v_mfma_f32_16x16x32_bf16 v[118:121], v[150:153], v[166:169], v[118:121]
	v_mfma_f32_16x16x32_bf16 v[114:117], v[158:161], v[166:169], v[114:117]
	v_mfma_f32_16x16x32_bf16 v[102:105], v[150:153], v[174:177], v[102:105]
	v_mfma_f32_16x16x32_bf16 v[98:101], v[158:161], v[174:177], v[98:101]
	v_mfma_f32_16x16x32_bf16 v[86:89], v[150:153], v[182:185], v[86:89]
	v_mfma_f32_16x16x32_bf16 v[82:85], v[158:161], v[182:185], v[82:85]
	v_mfma_f32_16x16x32_bf16 v[70:73], v[150:153], v[190:193], v[70:73]
	v_mfma_f32_16x16x32_bf16 v[66:69], v[158:161], v[190:193], v[66:69]
	v_mfma_f32_16x16x32_bf16 v[118:121], v[154:157], v[170:173], v[118:121]
	v_mfma_f32_16x16x32_bf16 v[114:117], v[162:165], v[170:173], v[114:117]
	v_mfma_f32_16x16x32_bf16 v[102:105], v[154:157], v[178:181], v[102:105]
	v_mfma_f32_16x16x32_bf16 v[98:101], v[162:165], v[178:181], v[98:101]
	v_mfma_f32_16x16x32_bf16 v[86:89], v[154:157], v[186:189], v[86:89]
	v_mfma_f32_16x16x32_bf16 v[82:85], v[162:165], v[186:189], v[82:85]
	v_mfma_f32_16x16x32_bf16 v[70:73], v[154:157], v[206:209], v[70:73]
	v_mfma_f32_16x16x32_bf16 v[66:69], v[162:165], v[206:209], v[66:69]
	s_barrier
; #define PG8_STAGE(bufoff, gbase, voff) do { _Pragma("unroll") for (int _i = 0; _i < 2; ++_i) \
;         __builtin_amdgcn_global_load_lds((const unsigned*)((const char*)(gbase) + (voff)[_i]), (LAS unsigned*)(lds + (bufoff) + ldsw + _i * 8192), 16, 0, 0); } while (0)
; #define PG8_LDA(dst, b, h) do { _Pragma("unroll") for (int m = 0; m < 4; ++m) _Pragma("unroll") for (int k = 0; k < 2; ++k) dst[m][k] = *(const LAS bf16x8*)(lds + PG8_SA(b, h) + aoff + m * 2048 + k * 1024); } while (0)
; #define PG8_MMA(ai, bj, At, Bt) do { __builtin_amdgcn_s_setprio(1); _Pragma("unroll") for (int m = 0; m < 4; ++m) _Pragma("unroll") for (int n = 0; n < 2; ++n) _Pragma("unroll") for (int k = 0; k < 2; ++k) \
;         acc[ai][bj][m][n] = __builtin_amdgcn_mfma_f32_16x16x32_bf16(Bt[n][k], At[m][k], acc[ai][bj][m][n], 0, 0, 0); __builtin_amdgcn_s_setprio(0); } while (0)
; #define PG8_WAIT_V(n) asm volatile("s_waitcnt vmcnt(" #n ")" ::: "memory")
; #define PG8_WAIT_L(n) asm volatile("s_waitcnt lgkmcnt(" #n ")" ::: "memory")
; #define PG8_BAR __builtin_amdgcn_s_barrier()
; #define PG8_SCHED __builtin_amdgcn_sched_barrier(0)
; DI void gemm_phase(LAS unsigned char* lds, const Sched& S, const Epi& Ep) {
;     ...
;             PG8_LDA(At, 1, 1); PG8_STAGE(PG8_SB(1, 0), b3, voffB); PG8_STAGE(PG8_SB(1, 1), b3 + hstepB, voffB); PG8_STAGE(PG8_SA(1, 0), a3, voffA);
;             PG8_WAIT_V(8); PG8_WAIT_L(0); PG8_BAR; PG8_MMA(1, 0, At, B0); PG8_MMA(1, 1, At, B1); PG8_BAR; PG8_SCHED;
;         }
;         if (align_epi) { if (wr == 0) PG8_BAR; }
	s_add_i32 s8, s8, s19
	v_lshl_add_u64 v[210:211], v[210:211], 0, s[26:27]
	s_mov_b32 m0, s8
	ds_read_b128 v[166:169], v249 offset:49152
	ds_read_b128 v[170:173], v249 offset:50176
	ds_read_b128 v[174:177], v249 offset:51200
	ds_read_b128 v[178:181], v249 offset:52224
	ds_read_b128 v[182:185], v249 offset:53248
	ds_read_b128 v[186:189], v249 offset:54272
	ds_read_b128 v[190:193], v249 offset:55296
	ds_read_b128 v[206:209], v249 offset:56320
	global_load_lds_dwordx4 v[210:211], off
	v_lshl_add_u64 v[210:211], v[212:213], 0, s[26:27]
	s_add_i32 m0, s8, 0x2000
	s_add_i32 s8, s24, s19
	global_load_lds_dwordx4 v[210:211], off
	v_lshl_add_u64 v[210:211], v[214:215], 0, s[26:27]
	s_mov_b32 m0, s8
	s_nop 0
	global_load_lds_dwordx4 v[210:211], off
	v_lshl_add_u64 v[210:211], v[216:217], 0, s[26:27]
	s_add_i32 m0, s8, 0x2000
	s_nop 0
	global_load_lds_dwordx4 v[210:211], off
	v_lshl_add_u64 v[210:211], v[218:219], 0, s[26:27]
	s_mov_b32 m0, s89
	s_nop 0
	global_load_lds_dwordx4 v[210:211], off
	v_lshl_add_u64 v[210:211], v[220:221], 0, s[26:27]
	s_mov_b32 m0, s34
	s_nop 0
	global_load_lds_dwordx4 v[210:211], off
	s_waitcnt vmcnt(8)
	s_waitcnt lgkmcnt(0)
	s_barrier
	s_waitcnt lgkmcnt(0)
	v_mfma_f32_16x16x32_bf16 v[62:65], v[134:137], v[166:169], v[62:65]
	v_mfma_f32_16x16x32_bf16 v[58:61], v[142:145], v[166:169], v[58:61]
	v_mfma_f32_16x16x32_bf16 v[46:49], v[134:137], v[174:177], v[46:49]
	v_mfma_f32_16x16x32_bf16 v[42:45], v[142:145], v[174:177], v[42:45]
	v_mfma_f32_16x16x32_bf16 v[30:33], v[134:137], v[182:185], v[30:33]
	v_mfma_f32_16x16x32_bf16 v[26:29], v[142:145], v[182:185], v[26:29]
	v_mfma_f32_16x16x32_bf16 v[14:17], v[134:137], v[190:193], v[14:17]
	v_mfma_f32_16x16x32_bf16 v[10:13], v[142:145], v[190:193], v[10:13]
	v_mfma_f32_16x16x32_bf16 v[62:65], v[138:141], v[170:173], v[62:65]
	v_mfma_f32_16x16x32_bf16 v[58:61], v[146:149], v[170:173], v[58:61]
	v_mfma_f32_16x16x32_bf16 v[46:49], v[138:141], v[178:181], v[46:49]
	v_mfma_f32_16x16x32_bf16 v[42:45], v[146:149], v[178:181], v[42:45]
	v_mfma_f32_16x16x32_bf16 v[30:33], v[138:141], v[186:189], v[30:33]
	v_mfma_f32_16x16x32_bf16 v[26:29], v[146:149], v[186:189], v[26:29]
	v_mfma_f32_16x16x32_bf16 v[14:17], v[138:141], v[206:209], v[14:17]
	v_mfma_f32_16x16x32_bf16 v[10:13], v[146:149], v[206:209], v[10:13]
	v_mfma_f32_16x16x32_bf16 v[54:57], v[150:153], v[166:169], v[54:57]
	v_mfma_f32_16x16x32_bf16 v[50:53], v[158:161], v[166:169], v[50:53]
	v_mfma_f32_16x16x32_bf16 v[38:41], v[150:153], v[174:177], v[38:41]
	v_mfma_f32_16x16x32_bf16 v[34:37], v[158:161], v[174:177], v[34:37]
	v_mfma_f32_16x16x32_bf16 v[22:25], v[150:153], v[182:185], v[22:25]
	v_mfma_f32_16x16x32_bf16 v[18:21], v[158:161], v[182:185], v[18:21]
	v_mfma_f32_16x16x32_bf16 v[6:9], v[150:153], v[190:193], v[6:9]
	v_mfma_f32_16x16x32_bf16 v[2:5], v[158:161], v[190:193], v[2:5]
	v_mfma_f32_16x16x32_bf16 v[54:57], v[154:157], v[170:173], v[54:57]
	v_mfma_f32_16x16x32_bf16 v[50:53], v[162:165], v[170:173], v[50:53]
	v_mfma_f32_16x16x32_bf16 v[38:41], v[154:157], v[178:181], v[38:41]
	v_mfma_f32_16x16x32_bf16 v[34:37], v[162:165], v[178:181], v[34:37]
	v_mfma_f32_16x16x32_bf16 v[22:25], v[154:157], v[186:189], v[22:25]
	v_mfma_f32_16x16x32_bf16 v[18:21], v[162:165], v[186:189], v[18:21]
	v_mfma_f32_16x16x32_bf16 v[6:9], v[154:157], v[206:209], v[6:9]
	v_mfma_f32_16x16x32_bf16 v[2:5], v[162:165], v[206:209], v[2:5]
	s_add_u32 s44, s44, 0x100
	s_addc_u32 s45, s45, 0
	s_cmp_ge_u32 s3, s97
	s_barrier
	s_cbranch_scc0 .LBB0_370
	s_and_b64 vcc, exec, s[82:83]
	s_cbranch_vccz .LBB0_373
	s_barrier
